# grid barrier: non-leader workgroups wait on the cross-XCD release word directly; per-XCD release add removed
# baseline (speedup 1.0000x reference)
; __device__ __forceinline__ unsigned xb_ld(unsigned* p)              { return __hip_atomic_load(p, __ATOMIC_RELAXED, __HIP_MEMORY_SCOPE_AGENT); }
; __device__ __forceinline__ unsigned xb_add(unsigned* p, unsigned v) { return __hip_atomic_fetch_add(p, v, __ATOMIC_RELAXED, __HIP_MEMORY_SCOPE_AGENT); }
; #define XB_SPIN(cond, bar) do { unsigned _sp = 0; while (cond) { __builtin_amdgcn_s_sleep(1); \
;     if ((++_sp & 255u) == 0u) { if (xb_ld(&(bar)[XB_TMO])) break; if (_sp > XB_SPIN_CAP) { atomicAdd(&(bar)[XB_TMO], 1u); break; } } } } while (0)
; __device__ __forceinline__ void xcd_barrier(const XcdBarrier& b, int wave_id) {
;     ...
;         const unsigned old = xb_add(&bar[XB_XSUB(b.x)], 1u);
;         const unsigned gen = old / nloc;
;         if (old + 1u == (gen + 1u) * nloc) {
;             __builtin_amdgcn_fence(__ATOMIC_RELEASE, "agent");
;             asm volatile("s_waitcnt vmcnt(0)" ::: "memory");
;             const unsigned og = xb_add(&bar[XB_TOP], 1u);
;             const unsigned tg = og / nx;
;             if (og + 1u == (tg + 1u) * nx) xb_add(&bar[XB_TOPGEN], 1u);
;             else XB_SPIN(xb_ld(&bar[XB_TOPGEN]) == tg, bar);
;             __builtin_amdgcn_fence(__ATOMIC_ACQUIRE, "agent");
;             xb_add(&bar[XB_XGEN(b.x)], 1u);
;             asm volatile("s_waitcnt vmcnt(0)" ::: "memory");
;         } else {
;             XB_SPIN(xb_ld(&bar[XB_XGEN(b.x)]) == gen, bar);
;             __builtin_amdgcn_fence(__ATOMIC_ACQUIRE, "agent");
;             asm volatile("s_waitcnt vmcnt(0)" ::: "memory");
;         }
.LBB0_65:
	s_or_b64 exec, exec, s[18:19]
	v_cvt_f32_u32_e32 v4, v2
	s_waitcnt vmcnt(0)
	v_readfirstlane_b32 s8, v3
	v_sub_u32_e32 v3, 0, v2
	v_rcp_iflag_f32_e32 v4, v4
	v_add_u32_e32 v5, s8, v1
	v_mul_f32_e32 v4, 0x4f7ffffe, v4
	v_cvt_u32_f32_e32 v4, v4
	v_mul_lo_u32 v1, v3, v4
	v_mul_hi_u32 v1, v4, v1
	v_add_u32_e32 v1, v4, v1
	v_mul_hi_u32 v1, v5, v1
	v_mul_lo_u32 v3, v1, v2
	v_sub_u32_e32 v3, v5, v3
	v_add_u32_e32 v4, 1, v1
	v_cmp_ge_u32_e32 vcc, v3, v2
	s_nop 1
	v_cndmask_b32_e32 v1, v1, v4, vcc
	v_sub_u32_e32 v4, v3, v2
	v_cndmask_b32_e32 v3, v3, v4, vcc
	v_add_u32_e32 v4, 1, v1
	v_cmp_ge_u32_e32 vcc, v3, v2
	v_add_u32_e32 v3, 1, v5
	s_nop 0
	v_cndmask_b32_e32 v1, v1, v4, vcc
	v_mul_lo_u32 v4, v2, v1
	v_add_u32_e32 v2, v4, v2
	v_cmp_ne_u32_e32 vcc, v3, v2
	s_and_saveexec_b64 s[8:9], vcc
	s_xor_b64 s[8:9], exec, s[8:9]
	s_cbranch_execz .LBB0_79
	s_waitcnt lgkmcnt(0)
	v_mov_b32_e32 v0, 0
	s_add_u32 s22, s14, 0xff43500
	s_addc_u32 s23, s15, 0
	global_load_dword v0, v0, s[22:23] sc1
	s_waitcnt vmcnt(0)
	v_cmp_eq_u32_e32 vcc, v0, v1
	s_and_saveexec_b64 s[18:19], vcc
	s_cbranch_execz .LBB0_78
	s_add_u32 s20, s14, 0xff40200
	s_addc_u32 s21, s15, 0
	s_mov_b32 s26, 1
	s_mov_b64 s[30:31], 0
	v_mov_b32_e32 v0, 0
	s_branch .LBB0_69

; __device__ __forceinline__ unsigned xb_add(unsigned* p, unsigned v) { return __hip_atomic_fetch_add(p, v, __ATOMIC_RELAXED, __HIP_MEMORY_SCOPE_AGENT); }
; __device__ __forceinline__ void xcd_barrier(const XcdBarrier& b, int wave_id) {
;     ...
;             __builtin_amdgcn_fence(__ATOMIC_ACQUIRE, "agent");
;             xb_add(&bar[XB_XGEN(b.x)], 1u);
;             asm volatile("s_waitcnt vmcnt(0)" ::: "memory");
.LBB0_96:
	s_or_b64 exec, exec, s[8:9]
	s_mov_b64 s[8:9], exec
	v_mbcnt_lo_u32_b32 v0, s8, 0
	v_mbcnt_hi_u32_b32 v0, s9, v0
	v_cmp_eq_u32_e32 vcc, 0, v0
	s_waitcnt vmcnt(0)
	buffer_inv sc1
	s_and_saveexec_b64 s[18:19], vcc
	s_cbranch_execz .LBB0_98
	s_bcnt1_i32_b64 s8, s[8:9]
	v_mov_b32_e32 v0, 0x2000
	v_mov_b32_e32 v1, s8
	s_nop 0

; __device__ __forceinline__ unsigned xb_ld(unsigned* p)              { return __hip_atomic_load(p, __ATOMIC_RELAXED, __HIP_MEMORY_SCOPE_AGENT); }
; __device__ __forceinline__ unsigned xb_add(unsigned* p, unsigned v) { return __hip_atomic_fetch_add(p, v, __ATOMIC_RELAXED, __HIP_MEMORY_SCOPE_AGENT); }
; #define XB_SPIN(cond, bar) do { unsigned _sp = 0; while (cond) { __builtin_amdgcn_s_sleep(1); \
;     if ((++_sp & 255u) == 0u) { if (xb_ld(&(bar)[XB_TMO])) break; if (_sp > XB_SPIN_CAP) { atomicAdd(&(bar)[XB_TMO], 1u); break; } } } } while (0)
; __device__ __forceinline__ void xcd_barrier(const XcdBarrier& b, int wave_id) {
;     ...
;         const unsigned old = xb_add(&bar[XB_XSUB(b.x)], 1u);
;         const unsigned gen = old / nloc;
;         if (old + 1u == (gen + 1u) * nloc) {
;             __builtin_amdgcn_fence(__ATOMIC_RELEASE, "agent");
;             asm volatile("s_waitcnt vmcnt(0)" ::: "memory");
;             const unsigned og = xb_add(&bar[XB_TOP], 1u);
;             const unsigned tg = og / nx;
;             if (og + 1u == (tg + 1u) * nx) xb_add(&bar[XB_TOPGEN], 1u);
;             else XB_SPIN(xb_ld(&bar[XB_TOPGEN]) == tg, bar);
;             __builtin_amdgcn_fence(__ATOMIC_ACQUIRE, "agent");
;             xb_add(&bar[XB_XGEN(b.x)], 1u);
;             asm volatile("s_waitcnt vmcnt(0)" ::: "memory");
;         } else {
;             XB_SPIN(xb_ld(&bar[XB_XGEN(b.x)]) == gen, bar);
;             __builtin_amdgcn_fence(__ATOMIC_ACQUIRE, "agent");
;             asm volatile("s_waitcnt vmcnt(0)" ::: "memory");
;         }
.LBB0_225:
	s_or_b64 exec, exec, s[10:11]
	v_cvt_f32_u32_e32 v4, v2
	s_waitcnt vmcnt(0)
	v_readfirstlane_b32 s8, v3
	v_sub_u32_e32 v3, 0, v2
	v_rcp_iflag_f32_e32 v4, v4
	v_add_u32_e32 v5, s8, v1
	v_mul_f32_e32 v4, 0x4f7ffffe, v4
	v_cvt_u32_f32_e32 v4, v4
	v_mul_lo_u32 v1, v3, v4
	v_mul_hi_u32 v1, v4, v1
	v_add_u32_e32 v1, v4, v1
	v_mul_hi_u32 v1, v5, v1
	v_mul_lo_u32 v3, v1, v2
	v_sub_u32_e32 v3, v5, v3
	v_add_u32_e32 v4, 1, v1
	v_cmp_ge_u32_e32 vcc, v3, v2
	s_nop 1
	v_cndmask_b32_e32 v1, v1, v4, vcc
	v_sub_u32_e32 v4, v3, v2
	v_cndmask_b32_e32 v3, v3, v4, vcc
	v_add_u32_e32 v4, 1, v1
	v_cmp_ge_u32_e32 vcc, v3, v2
	v_add_u32_e32 v3, 1, v5
	s_nop 0
	v_cndmask_b32_e32 v1, v1, v4, vcc
	v_mul_lo_u32 v4, v2, v1
	v_add_u32_e32 v2, v4, v2
	v_cmp_ne_u32_e32 vcc, v3, v2
	s_and_saveexec_b64 s[8:9], vcc
	s_xor_b64 s[8:9], exec, s[8:9]
	s_cbranch_execz .LBB0_239
	s_waitcnt lgkmcnt(0)
	v_mov_b32_e32 v0, 0
	s_add_u32 s22, s14, 0xff43500
	s_addc_u32 s23, s15, 0
	global_load_dword v0, v0, s[22:23] sc1
	s_waitcnt vmcnt(0)
	v_cmp_eq_u32_e32 vcc, v0, v1
	s_and_saveexec_b64 s[10:11], vcc
	s_cbranch_execz .LBB0_238
	s_add_u32 s20, s14, 0xff40200
	s_addc_u32 s21, s15, 0
	s_mov_b32 s26, 1
	s_mov_b64 s[44:45], 0
	v_mov_b32_e32 v0, 0
	s_branch .LBB0_229

; __device__ __forceinline__ unsigned xb_add(unsigned* p, unsigned v) { return __hip_atomic_fetch_add(p, v, __ATOMIC_RELAXED, __HIP_MEMORY_SCOPE_AGENT); }
; __device__ __forceinline__ void xcd_barrier(const XcdBarrier& b, int wave_id) {
;     ...
;             __builtin_amdgcn_fence(__ATOMIC_ACQUIRE, "agent");
;             xb_add(&bar[XB_XGEN(b.x)], 1u);
;             asm volatile("s_waitcnt vmcnt(0)" ::: "memory");
.LBB0_256:
	s_or_b64 exec, exec, s[8:9]
	s_mov_b64 s[8:9], exec
	v_mbcnt_lo_u32_b32 v0, s8, 0
	v_mbcnt_hi_u32_b32 v0, s9, v0
	v_cmp_eq_u32_e32 vcc, 0, v0
	s_waitcnt vmcnt(0)
	buffer_inv sc1
	s_and_saveexec_b64 s[10:11], vcc
	s_cbranch_execz .LBB0_258
	s_bcnt1_i32_b64 s8, s[8:9]
	v_mov_b32_e32 v0, 0x2000
	v_mov_b32_e32 v1, s8
	s_nop 0

; __device__ __forceinline__ unsigned xb_ld(unsigned* p)              { return __hip_atomic_load(p, __ATOMIC_RELAXED, __HIP_MEMORY_SCOPE_AGENT); }
; __device__ __forceinline__ unsigned xb_add(unsigned* p, unsigned v) { return __hip_atomic_fetch_add(p, v, __ATOMIC_RELAXED, __HIP_MEMORY_SCOPE_AGENT); }
; #define XB_SPIN(cond, bar) do { unsigned _sp = 0; while (cond) { __builtin_amdgcn_s_sleep(1); \
;     if ((++_sp & 255u) == 0u) { if (xb_ld(&(bar)[XB_TMO])) break; if (_sp > XB_SPIN_CAP) { atomicAdd(&(bar)[XB_TMO], 1u); break; } } } } while (0)
; __device__ __forceinline__ void xcd_barrier(const XcdBarrier& b, int wave_id) {
;     ...
;         const unsigned old = xb_add(&bar[XB_XSUB(b.x)], 1u);
;         const unsigned gen = old / nloc;
;         if (old + 1u == (gen + 1u) * nloc) {
;             __builtin_amdgcn_fence(__ATOMIC_RELEASE, "agent");
;             asm volatile("s_waitcnt vmcnt(0)" ::: "memory");
;             const unsigned og = xb_add(&bar[XB_TOP], 1u);
;             const unsigned tg = og / nx;
;             if (og + 1u == (tg + 1u) * nx) xb_add(&bar[XB_TOPGEN], 1u);
;             else XB_SPIN(xb_ld(&bar[XB_TOPGEN]) == tg, bar);
;             __builtin_amdgcn_fence(__ATOMIC_ACQUIRE, "agent");
;             xb_add(&bar[XB_XGEN(b.x)], 1u);
;             asm volatile("s_waitcnt vmcnt(0)" ::: "memory");
;         } else {
;             XB_SPIN(xb_ld(&bar[XB_XGEN(b.x)]) == gen, bar);
;             __builtin_amdgcn_fence(__ATOMIC_ACQUIRE, "agent");
;             asm volatile("s_waitcnt vmcnt(0)" ::: "memory");
;         }
.LBB0_387:
	s_or_b64 exec, exec, s[22:23]
	v_cvt_f32_u32_e32 v4, v2
	s_waitcnt vmcnt(0)
	v_readfirstlane_b32 s6, v3
	v_sub_u32_e32 v3, 0, v2
	v_rcp_iflag_f32_e32 v4, v4
	v_add_u32_e32 v5, s6, v1
	v_mul_f32_e32 v4, 0x4f7ffffe, v4
	v_cvt_u32_f32_e32 v4, v4
	v_mul_lo_u32 v1, v3, v4
	v_mul_hi_u32 v1, v4, v1
	v_add_u32_e32 v1, v4, v1
	v_mul_hi_u32 v1, v5, v1
	v_mul_lo_u32 v3, v1, v2
	v_sub_u32_e32 v3, v5, v3
	v_add_u32_e32 v4, 1, v1
	v_cmp_ge_u32_e32 vcc, v3, v2
	s_nop 1
	v_cndmask_b32_e32 v1, v1, v4, vcc
	v_sub_u32_e32 v4, v3, v2
	v_cndmask_b32_e32 v3, v3, v4, vcc
	v_add_u32_e32 v4, 1, v1
	v_cmp_ge_u32_e32 vcc, v3, v2
	v_add_u32_e32 v3, 1, v5
	s_nop 0
	v_cndmask_b32_e32 v1, v1, v4, vcc
	v_mul_lo_u32 v4, v2, v1
	v_add_u32_e32 v2, v4, v2
	v_cmp_ne_u32_e32 vcc, v3, v2
	s_and_saveexec_b64 s[6:7], vcc
	s_xor_b64 s[20:21], exec, s[6:7]
	s_cbranch_execz .LBB0_401
	s_waitcnt lgkmcnt(0)
	v_mov_b32_e32 v0, 0
	s_add_u32 s44, s14, 0xff43500
	s_addc_u32 s45, s15, 0
	global_load_dword v0, v0, s[44:45] sc1
	s_waitcnt vmcnt(0)
	v_cmp_eq_u32_e32 vcc, v0, v1
	s_and_saveexec_b64 s[22:23], vcc
	s_cbranch_execz .LBB0_400
	s_add_u32 s42, s14, 0xff40200
	s_addc_u32 s43, s15, 0
	s_mov_b32 s6, 1
	s_mov_b64 s[46:47], 0
	v_mov_b32_e32 v0, 0
	s_branch .LBB0_391

; __device__ __forceinline__ unsigned xb_add(unsigned* p, unsigned v) { return __hip_atomic_fetch_add(p, v, __ATOMIC_RELAXED, __HIP_MEMORY_SCOPE_AGENT); }
; __device__ __forceinline__ void xcd_barrier(const XcdBarrier& b, int wave_id) {
;     ...
;             __builtin_amdgcn_fence(__ATOMIC_ACQUIRE, "agent");
;             xb_add(&bar[XB_XGEN(b.x)], 1u);
;             asm volatile("s_waitcnt vmcnt(0)" ::: "memory");
.LBB0_418:
	s_or_b64 exec, exec, s[20:21]
	s_mov_b64 s[20:21], exec
	v_mbcnt_lo_u32_b32 v0, s20, 0
	v_mbcnt_hi_u32_b32 v0, s21, v0
	v_cmp_eq_u32_e32 vcc, 0, v0
	s_waitcnt vmcnt(0)
	buffer_inv sc1
	s_and_saveexec_b64 s[22:23], vcc
	s_cbranch_execz .LBB0_420
	s_bcnt1_i32_b64 s6, s[20:21]
	v_mov_b32_e32 v0, 0x2000
	v_mov_b32_e32 v1, s6
	s_nop 0

; __device__ __forceinline__ unsigned xb_ld(unsigned* p)              { return __hip_atomic_load(p, __ATOMIC_RELAXED, __HIP_MEMORY_SCOPE_AGENT); }
; __device__ __forceinline__ unsigned xb_add(unsigned* p, unsigned v) { return __hip_atomic_fetch_add(p, v, __ATOMIC_RELAXED, __HIP_MEMORY_SCOPE_AGENT); }
; #define XB_SPIN(cond, bar) do { unsigned _sp = 0; while (cond) { __builtin_amdgcn_s_sleep(1); \
;     if ((++_sp & 255u) == 0u) { if (xb_ld(&(bar)[XB_TMO])) break; if (_sp > XB_SPIN_CAP) { atomicAdd(&(bar)[XB_TMO], 1u); break; } } } } while (0)
; __device__ __forceinline__ void xcd_barrier(const XcdBarrier& b, int wave_id) {
;     ...
;         const unsigned old = xb_add(&bar[XB_XSUB(b.x)], 1u);
;         const unsigned gen = old / nloc;
;         if (old + 1u == (gen + 1u) * nloc) {
;             __builtin_amdgcn_fence(__ATOMIC_RELEASE, "agent");
;             asm volatile("s_waitcnt vmcnt(0)" ::: "memory");
;             const unsigned og = xb_add(&bar[XB_TOP], 1u);
;             const unsigned tg = og / nx;
;             if (og + 1u == (tg + 1u) * nx) xb_add(&bar[XB_TOPGEN], 1u);
;             else XB_SPIN(xb_ld(&bar[XB_TOPGEN]) == tg, bar);
;             __builtin_amdgcn_fence(__ATOMIC_ACQUIRE, "agent");
;             xb_add(&bar[XB_XGEN(b.x)], 1u);
;             asm volatile("s_waitcnt vmcnt(0)" ::: "memory");
;         } else {
;             XB_SPIN(xb_ld(&bar[XB_XGEN(b.x)]) == gen, bar);
;             __builtin_amdgcn_fence(__ATOMIC_ACQUIRE, "agent");
;             asm volatile("s_waitcnt vmcnt(0)" ::: "memory");
;         }
.LBB0_470:
	s_or_b64 exec, exec, s[22:23]
	v_cvt_f32_u32_e32 v4, v2
	s_waitcnt vmcnt(0)
	v_readfirstlane_b32 s6, v3
	v_sub_u32_e32 v3, 0, v2
	v_rcp_iflag_f32_e32 v4, v4
	v_add_u32_e32 v5, s6, v1
	v_mul_f32_e32 v4, 0x4f7ffffe, v4
	v_cvt_u32_f32_e32 v4, v4
	v_mul_lo_u32 v1, v3, v4
	v_mul_hi_u32 v1, v4, v1
	v_add_u32_e32 v1, v4, v1
	v_mul_hi_u32 v1, v5, v1
	v_mul_lo_u32 v3, v1, v2
	v_sub_u32_e32 v3, v5, v3
	v_add_u32_e32 v4, 1, v1
	v_cmp_ge_u32_e32 vcc, v3, v2
	s_nop 1
	v_cndmask_b32_e32 v1, v1, v4, vcc
	v_sub_u32_e32 v4, v3, v2
	v_cndmask_b32_e32 v3, v3, v4, vcc
	v_add_u32_e32 v4, 1, v1
	v_cmp_ge_u32_e32 vcc, v3, v2
	v_add_u32_e32 v3, 1, v5
	s_nop 0
	v_cndmask_b32_e32 v1, v1, v4, vcc
	v_mul_lo_u32 v4, v2, v1
	v_add_u32_e32 v2, v4, v2
	v_cmp_ne_u32_e32 vcc, v3, v2
	s_and_saveexec_b64 s[6:7], vcc
	s_xor_b64 s[10:11], exec, s[6:7]
	s_cbranch_execz .LBB0_484
	s_waitcnt lgkmcnt(0)
	v_mov_b32_e32 v0, 0
	s_add_u32 s40, s14, 0xff43500
	s_addc_u32 s41, s15, 0
	global_load_dword v0, v0, s[40:41] sc1
	s_waitcnt vmcnt(0)
	v_cmp_eq_u32_e32 vcc, v0, v1
	s_and_saveexec_b64 s[22:23], vcc
	s_cbranch_execz .LBB0_483
	s_add_u32 s38, s14, 0xff40200
	s_addc_u32 s39, s15, 0
	s_mov_b32 s6, 1
	s_mov_b64 s[42:43], 0
	v_mov_b32_e32 v0, 0
	s_branch .LBB0_474

; __device__ __forceinline__ unsigned xb_add(unsigned* p, unsigned v) { return __hip_atomic_fetch_add(p, v, __ATOMIC_RELAXED, __HIP_MEMORY_SCOPE_AGENT); }
; __device__ __forceinline__ void xcd_barrier(const XcdBarrier& b, int wave_id) {
;     ...
;             __builtin_amdgcn_fence(__ATOMIC_ACQUIRE, "agent");
;             xb_add(&bar[XB_XGEN(b.x)], 1u);
;             asm volatile("s_waitcnt vmcnt(0)" ::: "memory");
.LBB0_501:
	s_or_b64 exec, exec, s[10:11]
	s_mov_b64 s[10:11], exec
	v_mbcnt_lo_u32_b32 v0, s10, 0
	v_mbcnt_hi_u32_b32 v0, s11, v0
	v_cmp_eq_u32_e32 vcc, 0, v0
	s_waitcnt vmcnt(0)
	buffer_inv sc1
	s_and_saveexec_b64 s[22:23], vcc
	s_cbranch_execz .LBB0_503
	s_bcnt1_i32_b64 s6, s[10:11]
	v_mov_b32_e32 v0, 0x2000
	v_mov_b32_e32 v1, s6
	s_nop 0

; __device__ __forceinline__ unsigned xb_ld(unsigned* p)              { return __hip_atomic_load(p, __ATOMIC_RELAXED, __HIP_MEMORY_SCOPE_AGENT); }
; __device__ __forceinline__ unsigned xb_add(unsigned* p, unsigned v) { return __hip_atomic_fetch_add(p, v, __ATOMIC_RELAXED, __HIP_MEMORY_SCOPE_AGENT); }
; #define XB_SPIN(cond, bar) do { unsigned _sp = 0; while (cond) { __builtin_amdgcn_s_sleep(1); \
;     if ((++_sp & 255u) == 0u) { if (xb_ld(&(bar)[XB_TMO])) break; if (_sp > XB_SPIN_CAP) { atomicAdd(&(bar)[XB_TMO], 1u); break; } } } } while (0)
; __device__ __forceinline__ void xcd_barrier(const XcdBarrier& b, int wave_id) {
;     ...
;         const unsigned old = xb_add(&bar[XB_XSUB(b.x)], 1u);
;         const unsigned gen = old / nloc;
;         if (old + 1u == (gen + 1u) * nloc) {
;             __builtin_amdgcn_fence(__ATOMIC_RELEASE, "agent");
;             asm volatile("s_waitcnt vmcnt(0)" ::: "memory");
;             const unsigned og = xb_add(&bar[XB_TOP], 1u);
;             const unsigned tg = og / nx;
;             if (og + 1u == (tg + 1u) * nx) xb_add(&bar[XB_TOPGEN], 1u);
;             else XB_SPIN(xb_ld(&bar[XB_TOPGEN]) == tg, bar);
;             __builtin_amdgcn_fence(__ATOMIC_ACQUIRE, "agent");
;             xb_add(&bar[XB_XGEN(b.x)], 1u);
;             asm volatile("s_waitcnt vmcnt(0)" ::: "memory");
;         } else {
;             XB_SPIN(xb_ld(&bar[XB_XGEN(b.x)]) == gen, bar);
;             __builtin_amdgcn_fence(__ATOMIC_ACQUIRE, "agent");
;             asm volatile("s_waitcnt vmcnt(0)" ::: "memory");
;         }
.LBB0_578:
	s_or_b64 exec, exec, s[22:23]
	v_cvt_f32_u32_e32 v4, v2
	s_waitcnt vmcnt(0)
	v_readfirstlane_b32 s8, v3
	v_sub_u32_e32 v3, 0, v2
	v_rcp_iflag_f32_e32 v4, v4
	v_add_u32_e32 v5, s8, v1
	v_mul_f32_e32 v4, 0x4f7ffffe, v4
	v_cvt_u32_f32_e32 v4, v4
	v_mul_lo_u32 v1, v3, v4
	v_mul_hi_u32 v1, v4, v1
	v_add_u32_e32 v1, v4, v1
	v_mul_hi_u32 v1, v5, v1
	v_mul_lo_u32 v3, v1, v2
	v_sub_u32_e32 v3, v5, v3
	v_add_u32_e32 v4, 1, v1
	v_cmp_ge_u32_e32 vcc, v3, v2
	s_nop 1
	v_cndmask_b32_e32 v1, v1, v4, vcc
	v_sub_u32_e32 v4, v3, v2
	v_cndmask_b32_e32 v3, v3, v4, vcc
	v_add_u32_e32 v4, 1, v1
	v_cmp_ge_u32_e32 vcc, v3, v2
	v_add_u32_e32 v3, 1, v5
	s_nop 0
	v_cndmask_b32_e32 v1, v1, v4, vcc
	v_mul_lo_u32 v4, v2, v1
	v_add_u32_e32 v2, v4, v2
	v_cmp_ne_u32_e32 vcc, v3, v2
	s_and_saveexec_b64 s[8:9], vcc
	s_xor_b64 s[8:9], exec, s[8:9]
	s_cbranch_execz .LBB0_592
	s_waitcnt lgkmcnt(0)
	v_mov_b32_e32 v0, 0
	s_add_u32 s40, s14, 0xff43500
	s_addc_u32 s41, s15, 0
	global_load_dword v0, v0, s[40:41] sc1
	s_waitcnt vmcnt(0)
	v_cmp_eq_u32_e32 vcc, v0, v1
	s_and_saveexec_b64 s[22:23], vcc
	s_cbranch_execz .LBB0_591
	s_add_u32 s38, s14, 0xff40200
	s_addc_u32 s39, s15, 0
	s_mov_b32 s26, 1
	s_mov_b64 s[42:43], 0
	v_mov_b32_e32 v0, 0
	s_branch .LBB0_582

; __device__ __forceinline__ unsigned xb_add(unsigned* p, unsigned v) { return __hip_atomic_fetch_add(p, v, __ATOMIC_RELAXED, __HIP_MEMORY_SCOPE_AGENT); }
; __device__ __forceinline__ void xcd_barrier(const XcdBarrier& b, int wave_id) {
;     ...
;             __builtin_amdgcn_fence(__ATOMIC_ACQUIRE, "agent");
;             xb_add(&bar[XB_XGEN(b.x)], 1u);
;             asm volatile("s_waitcnt vmcnt(0)" ::: "memory");
.LBB0_609:
	s_or_b64 exec, exec, s[8:9]
	s_mov_b64 s[8:9], exec
	v_mbcnt_lo_u32_b32 v0, s8, 0
	v_mbcnt_hi_u32_b32 v0, s9, v0
	v_cmp_eq_u32_e32 vcc, 0, v0
	s_waitcnt vmcnt(0)
	buffer_inv sc1
	s_and_saveexec_b64 s[22:23], vcc
	s_cbranch_execz .LBB0_611
	s_bcnt1_i32_b64 s8, s[8:9]
	v_mov_b32_e32 v0, 0x2000
	v_mov_b32_e32 v1, s8
	s_nop 0

; __device__ __forceinline__ unsigned xb_ld(unsigned* p)              { return __hip_atomic_load(p, __ATOMIC_RELAXED, __HIP_MEMORY_SCOPE_AGENT); }
; __device__ __forceinline__ unsigned xb_add(unsigned* p, unsigned v) { return __hip_atomic_fetch_add(p, v, __ATOMIC_RELAXED, __HIP_MEMORY_SCOPE_AGENT); }
; #define XB_SPIN(cond, bar) do { unsigned _sp = 0; while (cond) { __builtin_amdgcn_s_sleep(1); \
;     if ((++_sp & 255u) == 0u) { if (xb_ld(&(bar)[XB_TMO])) break; if (_sp > XB_SPIN_CAP) { atomicAdd(&(bar)[XB_TMO], 1u); break; } } } } while (0)
; __device__ __forceinline__ void xcd_barrier(const XcdBarrier& b, int wave_id) {
;     ...
;         const unsigned old = xb_add(&bar[XB_XSUB(b.x)], 1u);
;         const unsigned gen = old / nloc;
;         if (old + 1u == (gen + 1u) * nloc) {
;             __builtin_amdgcn_fence(__ATOMIC_RELEASE, "agent");
;             asm volatile("s_waitcnt vmcnt(0)" ::: "memory");
;             const unsigned og = xb_add(&bar[XB_TOP], 1u);
;             const unsigned tg = og / nx;
;             if (og + 1u == (tg + 1u) * nx) xb_add(&bar[XB_TOPGEN], 1u);
;             else XB_SPIN(xb_ld(&bar[XB_TOPGEN]) == tg, bar);
;             __builtin_amdgcn_fence(__ATOMIC_ACQUIRE, "agent");
;             xb_add(&bar[XB_XGEN(b.x)], 1u);
;             asm volatile("s_waitcnt vmcnt(0)" ::: "memory");
;         } else {
;             XB_SPIN(xb_ld(&bar[XB_XGEN(b.x)]) == gen, bar);
;             __builtin_amdgcn_fence(__ATOMIC_ACQUIRE, "agent");
;             asm volatile("s_waitcnt vmcnt(0)" ::: "memory");
;         }
.LBB0_674:
	s_or_b64 exec, exec, s[16:17]
	v_cvt_f32_u32_e32 v4, v2
	s_waitcnt vmcnt(0)
	v_readfirstlane_b32 s8, v3
	v_sub_u32_e32 v3, 0, v2
	v_rcp_iflag_f32_e32 v4, v4
	v_add_u32_e32 v5, s8, v1
	v_mul_f32_e32 v4, 0x4f7ffffe, v4
	v_cvt_u32_f32_e32 v4, v4
	v_mul_lo_u32 v1, v3, v4
	v_mul_hi_u32 v1, v4, v1
	v_add_u32_e32 v1, v4, v1
	v_mul_hi_u32 v1, v5, v1
	v_mul_lo_u32 v3, v1, v2
	v_sub_u32_e32 v3, v5, v3
	v_add_u32_e32 v4, 1, v1
	v_cmp_ge_u32_e32 vcc, v3, v2
	s_nop 1
	v_cndmask_b32_e32 v1, v1, v4, vcc
	v_sub_u32_e32 v4, v3, v2
	v_cndmask_b32_e32 v3, v3, v4, vcc
	v_add_u32_e32 v4, 1, v1
	v_cmp_ge_u32_e32 vcc, v3, v2
	v_add_u32_e32 v3, 1, v5
	s_nop 0
	v_cndmask_b32_e32 v1, v1, v4, vcc
	v_mul_lo_u32 v4, v2, v1
	v_add_u32_e32 v2, v4, v2
	v_cmp_ne_u32_e32 vcc, v3, v2
	s_and_saveexec_b64 s[8:9], vcc
	s_xor_b64 s[8:9], exec, s[8:9]
	s_cbranch_execz .LBB0_688
	s_waitcnt lgkmcnt(0)
	v_mov_b32_e32 v0, 0
	s_add_u32 s22, s14, 0xff43500
	s_addc_u32 s23, s15, 0
	global_load_dword v0, v0, s[22:23] sc1
	s_waitcnt vmcnt(0)
	v_cmp_eq_u32_e32 vcc, v0, v1
	s_and_saveexec_b64 s[16:17], vcc
	s_cbranch_execz .LBB0_687
	s_add_u32 s20, s14, 0xff40200
	s_addc_u32 s21, s15, 0
	s_mov_b32 s26, 1
	s_mov_b64 s[36:37], 0
	v_mov_b32_e32 v0, 0
	s_branch .LBB0_678

; __device__ __forceinline__ unsigned xb_add(unsigned* p, unsigned v) { return __hip_atomic_fetch_add(p, v, __ATOMIC_RELAXED, __HIP_MEMORY_SCOPE_AGENT); }
; __device__ __forceinline__ void xcd_barrier(const XcdBarrier& b, int wave_id) {
;     ...
;             __builtin_amdgcn_fence(__ATOMIC_ACQUIRE, "agent");
;             xb_add(&bar[XB_XGEN(b.x)], 1u);
;             asm volatile("s_waitcnt vmcnt(0)" ::: "memory");
.LBB0_705:
	s_or_b64 exec, exec, s[8:9]
	s_mov_b64 s[8:9], exec
	v_mbcnt_lo_u32_b32 v0, s8, 0
	v_mbcnt_hi_u32_b32 v0, s9, v0
	v_cmp_eq_u32_e32 vcc, 0, v0
	s_waitcnt vmcnt(0)
	buffer_inv sc1
	s_and_saveexec_b64 s[16:17], vcc
	s_cbranch_execz .LBB0_707
	s_bcnt1_i32_b64 s8, s[8:9]
	v_mov_b32_e32 v0, 0x2000
	v_mov_b32_e32 v1, s8
	s_nop 0

; __device__ __forceinline__ unsigned xb_ld(unsigned* p)              { return __hip_atomic_load(p, __ATOMIC_RELAXED, __HIP_MEMORY_SCOPE_AGENT); }
; __device__ __forceinline__ unsigned xb_add(unsigned* p, unsigned v) { return __hip_atomic_fetch_add(p, v, __ATOMIC_RELAXED, __HIP_MEMORY_SCOPE_AGENT); }
; #define XB_SPIN(cond, bar) do { unsigned _sp = 0; while (cond) { __builtin_amdgcn_s_sleep(1); \
;     if ((++_sp & 255u) == 0u) { if (xb_ld(&(bar)[XB_TMO])) break; if (_sp > XB_SPIN_CAP) { atomicAdd(&(bar)[XB_TMO], 1u); break; } } } } while (0)
; __device__ __forceinline__ void xcd_barrier(const XcdBarrier& b, int wave_id) {
;     ...
;         const unsigned old = xb_add(&bar[XB_XSUB(b.x)], 1u);
;         const unsigned gen = old / nloc;
;         if (old + 1u == (gen + 1u) * nloc) {
;             __builtin_amdgcn_fence(__ATOMIC_RELEASE, "agent");
;             asm volatile("s_waitcnt vmcnt(0)" ::: "memory");
;             const unsigned og = xb_add(&bar[XB_TOP], 1u);
;             const unsigned tg = og / nx;
;             if (og + 1u == (tg + 1u) * nx) xb_add(&bar[XB_TOPGEN], 1u);
;             else XB_SPIN(xb_ld(&bar[XB_TOPGEN]) == tg, bar);
;             __builtin_amdgcn_fence(__ATOMIC_ACQUIRE, "agent");
;             xb_add(&bar[XB_XGEN(b.x)], 1u);
;             asm volatile("s_waitcnt vmcnt(0)" ::: "memory");
;         } else {
;             XB_SPIN(xb_ld(&bar[XB_XGEN(b.x)]) == gen, bar);
;             __builtin_amdgcn_fence(__ATOMIC_ACQUIRE, "agent");
;             asm volatile("s_waitcnt vmcnt(0)" ::: "memory");
;         }
.LBB0_750:
	s_or_b64 exec, exec, s[18:19]
	v_cvt_f32_u32_e32 v4, v2
	s_waitcnt vmcnt(0)
	v_readfirstlane_b32 s3, v3
	v_sub_u32_e32 v3, 0, v2
	v_rcp_iflag_f32_e32 v4, v4
	v_add_u32_e32 v5, s3, v1
	v_mul_f32_e32 v4, 0x4f7ffffe, v4
	v_cvt_u32_f32_e32 v4, v4
	v_mul_lo_u32 v1, v3, v4
	v_mul_hi_u32 v1, v4, v1
	v_add_u32_e32 v1, v4, v1
	v_mul_hi_u32 v1, v5, v1
	v_mul_lo_u32 v3, v1, v2
	v_sub_u32_e32 v3, v5, v3
	v_add_u32_e32 v4, 1, v1
	v_cmp_ge_u32_e32 vcc, v3, v2
	s_nop 1
	v_cndmask_b32_e32 v1, v1, v4, vcc
	v_sub_u32_e32 v4, v3, v2
	v_cndmask_b32_e32 v3, v3, v4, vcc
	v_add_u32_e32 v4, 1, v1
	v_cmp_ge_u32_e32 vcc, v3, v2
	v_add_u32_e32 v3, 1, v5
	s_nop 0
	v_cndmask_b32_e32 v1, v1, v4, vcc
	v_mul_lo_u32 v4, v2, v1
	v_add_u32_e32 v2, v4, v2
	v_cmp_ne_u32_e32 vcc, v3, v2
	s_and_saveexec_b64 s[16:17], vcc
	s_xor_b64 s[16:17], exec, s[16:17]
	s_cbranch_execz .LBB0_764
	s_waitcnt lgkmcnt(0)
	v_mov_b32_e32 v0, 0
	s_add_u32 s22, s14, 0xff43500
	s_addc_u32 s23, s15, 0
	global_load_dword v0, v0, s[22:23] sc1
	s_waitcnt vmcnt(0)
	v_cmp_eq_u32_e32 vcc, v0, v1
	s_and_saveexec_b64 s[18:19], vcc
	s_cbranch_execz .LBB0_763
	s_add_u32 s20, s14, 0xff40200
	s_addc_u32 s21, s15, 0
	s_mov_b32 s3, 1
	s_mov_b64 s[26:27], 0
	v_mov_b32_e32 v0, 0
	s_branch .LBB0_754

; __device__ __forceinline__ unsigned xb_add(unsigned* p, unsigned v) { return __hip_atomic_fetch_add(p, v, __ATOMIC_RELAXED, __HIP_MEMORY_SCOPE_AGENT); }
; __device__ __forceinline__ void xcd_barrier(const XcdBarrier& b, int wave_id) {
;     ...
;             __builtin_amdgcn_fence(__ATOMIC_ACQUIRE, "agent");
;             xb_add(&bar[XB_XGEN(b.x)], 1u);
;             asm volatile("s_waitcnt vmcnt(0)" ::: "memory");
.LBB0_781:
	s_or_b64 exec, exec, s[14:15]
	s_mov_b64 s[14:15], exec
	v_mbcnt_lo_u32_b32 v0, s14, 0
	v_mbcnt_hi_u32_b32 v0, s15, v0
	v_cmp_eq_u32_e32 vcc, 0, v0
	s_waitcnt vmcnt(0)
	buffer_inv sc1
	s_and_saveexec_b64 s[16:17], vcc
	s_cbranch_execz .LBB0_783
	s_bcnt1_i32_b64 s3, s[14:15]
	v_mov_b32_e32 v0, 0x2000
	v_mov_b32_e32 v1, s3
	s_nop 0
